# P0: compress-bias reductions moved from workgroups 0..7 (26 transpose tiles) to 248..255 (25 tiles)
# baseline (speedup 1.0000x reference)
; __global__ void __launch_bounds__(512) mega(Params p) {
;     ...
;     if (bid < 8) {
;       const int l = bid >> 1, kv = bid & 1;
;       const float* pos = p.in[kv ? 7 : 4] + (size_t)l * 2048;
;       const float* w1 = p.in[kv ? 8 : 5] + (size_t)l * 2048 * 128;
;       const int n = tid & 127, part = tid >> 7;
;       float a = 0.f;
;       for (int k = part * 512; k < part * 512 + 512; ++k) a += pos[k] * w1[(size_t)k * 128 + n];
.LBB0_216:
	s_or_b64 exec, exec, s[0:1]
	s_load_dwordx4 s[4:7], s[78:79], 0xa0
	s_load_dwordx16 s[8:23], s[78:79], 0x0
	s_waitcnt lgkmcnt(0)
	s_add_u32 s0, s6, 0x1f400000
	s_addc_u32 s1, s7, 0
	v_writelane_b32 v253, s0, 10
	s_add_i32 s24, s76, 0xffffff08
	s_cmp_gt_i32 s24, -1
	s_nop 0
	v_writelane_b32 v253, s1, 11
	s_cbranch_scc0 .LBB0_222
	s_load_dwordx16 s[36:51], s[78:79], 0x40
	s_ashr_i32 s2, s24, 1
	s_ashr_i32 s3, s2, 31
	s_and_b32 s6, s24, 1
	s_lshl_b64 s[4:5], s[2:3], 13
	s_cmp_eq_u32 s6, 0
	s_waitcnt lgkmcnt(0)
	s_mov_b64 s[12:13], s[36:37]
	s_cselect_b32 s8, s17, s23
	s_cselect_b32 s9, s16, s22
	s_cselect_b32 s7, s19, s13
	s_cselect_b32 s6, s18, s12
	s_lshl_b64 s[2:3], s[2:3], 20
	v_lshlrev_b32_e32 v3, 2, v2
	v_and_b32_e32 v8, 0xfffffe00, v3
	s_add_u32 s4, s9, s4
	v_ashrrev_i32_e32 v9, 31, v8
	s_addc_u32 s5, s8, s5
	v_add_u32_e32 v5, -1, v8
	v_lshl_add_u64 v[6:7], v[8:9], 2, s[4:5]
	v_lshlrev_b64 v[8:9], 9, v[8:9]
	v_and_b32_e32 v10, 0x7f, v2
	v_lshl_add_u64 v[8:9], s[2:3], 0, v[8:9]
	v_lshl_or_b32 v8, v10, 2, v8
	v_or_b32_e32 v3, 0x1ff, v3
	v_lshl_add_u64 v[8:9], s[6:7], 0, v[8:9]
	v_mov_b32_e32 v10, 0
	s_mov_b32 s2, 0
	s_mov_b64 s[4:5], 0x1000
	s_mov_b64 s[6:7], 0x100
.Lc1_batch:
	global_load_dword v110, v[6:7], off
	global_load_dword v111, v[6:7], off offset:4
	global_load_dword v112, v[6:7], off offset:8
	global_load_dword v113, v[6:7], off offset:12
	global_load_dword v114, v[6:7], off offset:16
	global_load_dword v115, v[6:7], off offset:20
	global_load_dword v116, v[6:7], off offset:24
	global_load_dword v117, v[6:7], off offset:28
	global_load_dword v118, v[6:7], off offset:32
	global_load_dword v119, v[6:7], off offset:36
	global_load_dword v120, v[6:7], off offset:40
	global_load_dword v121, v[6:7], off offset:44
	global_load_dword v122, v[6:7], off offset:48
	global_load_dword v123, v[6:7], off offset:52
	global_load_dword v124, v[6:7], off offset:56
	global_load_dword v125, v[6:7], off offset:60
	global_load_dword v126, v[6:7], off offset:64
	global_load_dword v127, v[6:7], off offset:68
	global_load_dword v128, v[6:7], off offset:72
	global_load_dword v129, v[6:7], off offset:76
	global_load_dword v130, v[6:7], off offset:80
	global_load_dword v131, v[6:7], off offset:84
	global_load_dword v132, v[6:7], off offset:88
	global_load_dword v133, v[6:7], off offset:92
	global_load_dword v134, v[6:7], off offset:96
	global_load_dword v135, v[6:7], off offset:100
	global_load_dword v136, v[6:7], off offset:104
	global_load_dword v137, v[6:7], off offset:108
	global_load_dword v138, v[6:7], off offset:112
	global_load_dword v139, v[6:7], off offset:116
	global_load_dword v140, v[6:7], off offset:120
	global_load_dword v141, v[6:7], off offset:124
	global_load_dword v142, v[6:7], off offset:128
	global_load_dword v143, v[6:7], off offset:132
	global_load_dword v144, v[6:7], off offset:136
	global_load_dword v145, v[6:7], off offset:140
	global_load_dword v146, v[6:7], off offset:144
	global_load_dword v147, v[6:7], off offset:148
	global_load_dword v148, v[6:7], off offset:152
	global_load_dword v149, v[6:7], off offset:156
	global_load_dword v150, v[6:7], off offset:160
	global_load_dword v151, v[6:7], off offset:164
	global_load_dword v152, v[6:7], off offset:168
	global_load_dword v153, v[6:7], off offset:172
	global_load_dword v154, v[6:7], off offset:176
	global_load_dword v155, v[6:7], off offset:180
	global_load_dword v156, v[6:7], off offset:184
	global_load_dword v157, v[6:7], off offset:188
	global_load_dword v158, v[6:7], off offset:192
	global_load_dword v159, v[6:7], off offset:196
	global_load_dword v160, v[6:7], off offset:200
	global_load_dword v161, v[6:7], off offset:204
	global_load_dword v162, v[6:7], off offset:208
	global_load_dword v163, v[6:7], off offset:212
	global_load_dword v164, v[6:7], off offset:216
	global_load_dword v165, v[6:7], off offset:220
	global_load_dword v166, v[6:7], off offset:224
	global_load_dword v167, v[6:7], off offset:228
	global_load_dword v168, v[6:7], off offset:232
	global_load_dword v169, v[6:7], off offset:236
	global_load_dword v170, v[6:7], off offset:240
	global_load_dword v171, v[6:7], off offset:244
	global_load_dword v172, v[6:7], off offset:248
	global_load_dword v173, v[6:7], off offset:252
	global_load_dword v174, v[8:9], off
	global_load_dword v175, v[8:9], off offset:512
	global_load_dword v176, v[8:9], off offset:1024
	global_load_dword v177, v[8:9], off offset:1536
	global_load_dword v178, v[8:9], off offset:2048
	global_load_dword v179, v[8:9], off offset:2560
	global_load_dword v180, v[8:9], off offset:3072
	global_load_dword v181, v[8:9], off offset:3584
	v_lshl_add_u64 v[8:9], v[8:9], 0, s[4:5]
	global_load_dword v182, v[8:9], off
	global_load_dword v183, v[8:9], off offset:512
	global_load_dword v184, v[8:9], off offset:1024
	global_load_dword v185, v[8:9], off offset:1536
	global_load_dword v186, v[8:9], off offset:2048
	global_load_dword v187, v[8:9], off offset:2560
	global_load_dword v188, v[8:9], off offset:3072
	global_load_dword v189, v[8:9], off offset:3584
	v_lshl_add_u64 v[8:9], v[8:9], 0, s[4:5]
	global_load_dword v190, v[8:9], off
	global_load_dword v191, v[8:9], off offset:512
	global_load_dword v192, v[8:9], off offset:1024
	global_load_dword v193, v[8:9], off offset:1536
	global_load_dword v194, v[8:9], off offset:2048
	global_load_dword v195, v[8:9], off offset:2560
	global_load_dword v196, v[8:9], off offset:3072
	global_load_dword v197, v[8:9], off offset:3584
	v_lshl_add_u64 v[8:9], v[8:9], 0, s[4:5]
	global_load_dword v198, v[8:9], off
	global_load_dword v199, v[8:9], off offset:512
	global_load_dword v200, v[8:9], off offset:1024
; __global__ void __launch_bounds__(512) mega(Params p) {
;     ...
;       const int n = tid & 127, part = tid >> 7;
;       float a = 0.f;
;       for (int k = part * 512; k < part * 512 + 512; ++k) a += pos[k] * w1[(size_t)k * 128 + n];
;       float* red = (float*)lds;
;       __syncthreads();
;       red[tid] = a;
;       __syncthreads();
;       if (tid < 128) cx.c1[(l * 2 + kv) * 128 + tid] = red[tid] + red[tid + 128] + red[tid + 256] + red[tid + 384];
;       __syncthreads();
	global_load_dword v201, v[8:9], off offset:1536
	global_load_dword v202, v[8:9], off offset:2048
	global_load_dword v203, v[8:9], off offset:2560
	global_load_dword v204, v[8:9], off offset:3072
	global_load_dword v205, v[8:9], off offset:3584
	v_lshl_add_u64 v[8:9], v[8:9], 0, s[4:5]
	global_load_dword v206, v[8:9], off
	global_load_dword v207, v[8:9], off offset:512
	global_load_dword v208, v[8:9], off offset:1024
	global_load_dword v209, v[8:9], off offset:1536
	global_load_dword v210, v[8:9], off offset:2048
	global_load_dword v211, v[8:9], off offset:2560
	global_load_dword v212, v[8:9], off offset:3072
	global_load_dword v213, v[8:9], off offset:3584
	v_lshl_add_u64 v[8:9], v[8:9], 0, s[4:5]
	global_load_dword v214, v[8:9], off
	global_load_dword v215, v[8:9], off offset:512
	global_load_dword v216, v[8:9], off offset:1024
	global_load_dword v217, v[8:9], off offset:1536
	global_load_dword v218, v[8:9], off offset:2048
	global_load_dword v219, v[8:9], off offset:2560
	global_load_dword v220, v[8:9], off offset:3072
	global_load_dword v221, v[8:9], off offset:3584
	v_lshl_add_u64 v[8:9], v[8:9], 0, s[4:5]
	global_load_dword v222, v[8:9], off
	global_load_dword v223, v[8:9], off offset:512
	global_load_dword v224, v[8:9], off offset:1024
	global_load_dword v225, v[8:9], off offset:1536
	global_load_dword v226, v[8:9], off offset:2048
	global_load_dword v227, v[8:9], off offset:2560
	global_load_dword v228, v[8:9], off offset:3072
	global_load_dword v229, v[8:9], off offset:3584
	v_lshl_add_u64 v[8:9], v[8:9], 0, s[4:5]
	global_load_dword v230, v[8:9], off
	global_load_dword v231, v[8:9], off offset:512
	global_load_dword v232, v[8:9], off offset:1024
	global_load_dword v233, v[8:9], off offset:1536
	global_load_dword v234, v[8:9], off offset:2048
	global_load_dword v235, v[8:9], off offset:2560
	global_load_dword v236, v[8:9], off offset:3072
	global_load_dword v237, v[8:9], off offset:3584
	v_lshl_add_u64 v[8:9], v[8:9], 0, s[4:5]
	v_lshl_add_u64 v[6:7], v[6:7], 0, s[6:7]
	s_add_i32 s2, s2, 1
	s_waitcnt vmcnt(63)
	v_fmac_f32_e32 v10, v110, v174
	s_waitcnt vmcnt(62)
	v_fmac_f32_e32 v10, v111, v175
	s_waitcnt vmcnt(61)
	v_fmac_f32_e32 v10, v112, v176
	s_waitcnt vmcnt(60)
	v_fmac_f32_e32 v10, v113, v177
	s_waitcnt vmcnt(59)
	v_fmac_f32_e32 v10, v114, v178
	s_waitcnt vmcnt(58)
	v_fmac_f32_e32 v10, v115, v179
	s_waitcnt vmcnt(57)
	v_fmac_f32_e32 v10, v116, v180
	s_waitcnt vmcnt(56)
	v_fmac_f32_e32 v10, v117, v181
	s_waitcnt vmcnt(55)
	v_fmac_f32_e32 v10, v118, v182
	s_waitcnt vmcnt(54)
	v_fmac_f32_e32 v10, v119, v183
	s_waitcnt vmcnt(53)
	v_fmac_f32_e32 v10, v120, v184
	s_waitcnt vmcnt(52)
	v_fmac_f32_e32 v10, v121, v185
	s_waitcnt vmcnt(51)
	v_fmac_f32_e32 v10, v122, v186
	s_waitcnt vmcnt(50)
	v_fmac_f32_e32 v10, v123, v187
	s_waitcnt vmcnt(49)
	v_fmac_f32_e32 v10, v124, v188
	s_waitcnt vmcnt(48)
	v_fmac_f32_e32 v10, v125, v189
	s_waitcnt vmcnt(47)
	v_fmac_f32_e32 v10, v126, v190
	s_waitcnt vmcnt(46)
	v_fmac_f32_e32 v10, v127, v191
	s_waitcnt vmcnt(45)
	v_fmac_f32_e32 v10, v128, v192
	s_waitcnt vmcnt(44)
	v_fmac_f32_e32 v10, v129, v193
	s_waitcnt vmcnt(43)
	v_fmac_f32_e32 v10, v130, v194
	s_waitcnt vmcnt(42)
	v_fmac_f32_e32 v10, v131, v195
	s_waitcnt vmcnt(41)
	v_fmac_f32_e32 v10, v132, v196
	s_waitcnt vmcnt(40)
	v_fmac_f32_e32 v10, v133, v197
	s_waitcnt vmcnt(39)
	v_fmac_f32_e32 v10, v134, v198
	s_waitcnt vmcnt(38)
	v_fmac_f32_e32 v10, v135, v199
	s_waitcnt vmcnt(37)
	v_fmac_f32_e32 v10, v136, v200
	s_waitcnt vmcnt(36)
	v_fmac_f32_e32 v10, v137, v201
	s_waitcnt vmcnt(35)
	v_fmac_f32_e32 v10, v138, v202
	s_waitcnt vmcnt(34)
	v_fmac_f32_e32 v10, v139, v203
	s_waitcnt vmcnt(33)
	v_fmac_f32_e32 v10, v140, v204
	s_waitcnt vmcnt(32)
	v_fmac_f32_e32 v10, v141, v205
	s_waitcnt vmcnt(31)
	v_fmac_f32_e32 v10, v142, v206
	s_waitcnt vmcnt(30)
	v_fmac_f32_e32 v10, v143, v207
	s_waitcnt vmcnt(29)
	v_fmac_f32_e32 v10, v144, v208
	s_waitcnt vmcnt(28)
	v_fmac_f32_e32 v10, v145, v209
	s_waitcnt vmcnt(27)
	v_fmac_f32_e32 v10, v146, v210
	s_waitcnt vmcnt(26)
	v_fmac_f32_e32 v10, v147, v211
	s_waitcnt vmcnt(25)
	v_fmac_f32_e32 v10, v148, v212
	s_waitcnt vmcnt(24)
	v_fmac_f32_e32 v10, v149, v213
	s_waitcnt vmcnt(23)
	v_fmac_f32_e32 v10, v150, v214
	s_waitcnt vmcnt(22)
	v_fmac_f32_e32 v10, v151, v215
	s_waitcnt vmcnt(21)
	v_fmac_f32_e32 v10, v152, v216
	s_waitcnt vmcnt(20)
	v_fmac_f32_e32 v10, v153, v217
	s_waitcnt vmcnt(19)
	v_fmac_f32_e32 v10, v154, v218
	s_waitcnt vmcnt(18)
	v_fmac_f32_e32 v10, v155, v219
	s_waitcnt vmcnt(17)
	v_fmac_f32_e32 v10, v156, v220
	s_waitcnt vmcnt(16)
	v_fmac_f32_e32 v10, v157, v221
	s_waitcnt vmcnt(15)
	v_fmac_f32_e32 v10, v158, v222
	s_waitcnt vmcnt(14)
	v_fmac_f32_e32 v10, v159, v223
	s_waitcnt vmcnt(13)
	v_fmac_f32_e32 v10, v160, v224
	s_waitcnt vmcnt(12)
	v_fmac_f32_e32 v10, v161, v225
	s_waitcnt vmcnt(11)
	v_fmac_f32_e32 v10, v162, v226
	s_waitcnt vmcnt(10)
	v_fmac_f32_e32 v10, v163, v227
	s_waitcnt vmcnt(9)
	v_fmac_f32_e32 v10, v164, v228
	s_waitcnt vmcnt(8)
	v_fmac_f32_e32 v10, v165, v229
	s_waitcnt vmcnt(7)
	v_fmac_f32_e32 v10, v166, v230
	s_waitcnt vmcnt(6)
	v_fmac_f32_e32 v10, v167, v231
	s_waitcnt vmcnt(5)
	v_fmac_f32_e32 v10, v168, v232
	s_waitcnt vmcnt(4)
	v_fmac_f32_e32 v10, v169, v233
	s_waitcnt vmcnt(3)
	v_fmac_f32_e32 v10, v170, v234
	s_waitcnt vmcnt(2)
	v_fmac_f32_e32 v10, v171, v235
	s_waitcnt vmcnt(1)
	v_fmac_f32_e32 v10, v172, v236
	s_waitcnt vmcnt(0)
	v_fmac_f32_e32 v10, v173, v237
	s_cmp_lt_u32 s2, 8
	s_cbranch_scc1 .Lc1_batch
	s_movk_i32 s2, 0x80
	v_lshl_add_u32 v3, v2, 2, 0
	v_cmp_gt_i32_e32 vcc, s2, v2
	s_barrier
	ds_write_b32 v3, v10
	s_waitcnt lgkmcnt(0)
	s_barrier
	s_and_saveexec_b64 s[2:3], vcc
	s_cbranch_execz .LBB0_221
	ds_read2st64_b32 v[6:7], v3 offset1:2
	ds_read2st64_b32 v[2:3], v3 offset0:4 offset1:6
	s_mul_i32 s4, s76, 0xfffffe80
	s_add_i32 s4, s4, 0xffff8400
	v_add_u32_e32 v4, s4, v4
	v_readlane_b32 s0, v253, 10
	s_waitcnt lgkmcnt(1)
	v_add_f32_e32 v6, v6, v7
	v_ashrrev_i32_e32 v5, 31, v4
	s_waitcnt lgkmcnt(0)
	v_add_f32_e32 v2, v6, v2
	v_readlane_b32 s1, v253, 11
	v_add_f32_e32 v6, v2, v3
	s_nop 0
	v_lshl_add_u64 v[2:3], v[4:5], 2, s[0:1]
	global_store_dword v[2:3], v6, off
